# P7 main loop: one static s_setprio 1 for waves 4-7, per-segment priority flips replaced by s_nop (size-neutral), placement kept
# speedup vs baseline: 1.0127x; 1.0089x over previous
; template <class Epi, class Sched, bool ALIGN_EPI = false, bool SP2 = false>
; __device__ __forceinline__ void gemm_phase(PG8_LAS unsigned char* lds, const Gemm g, const Sched& S, const Epi& E) {
;     ...
;         const bool has_next = S.next(ui + 1, nxt);
;         const char* nA = has_next ? (const char*)g.A + (size_t)nxt.pm * tstep + (size_t)nxt.kt0 * kstep : cA; const char* nB = has_next ? (const char*)g.Bt + (size_t)nxt.pn * tstep + (size_t)nxt.kt0 * kstep : cB;
.LBB0_1400:
	s_ashr_i32 s63, s62, 31
	s_lshl_b64 s[2:3], s[62:63], 20
	s_add_u32 s45, s12, s2
	s_addc_u32 s63, s13, s3
	s_ashr_i32 s77, s76, 31
	s_lshl_b64 s[2:3], s[76:77], 7
	s_add_u32 s78, s45, s2
	s_addc_u32 s79, s63, s3
	s_and_b64 vcc, exec, s[42:43]
	s_mov_b64 s[80:81], s[22:23]
	s_cbranch_vccz .LBB0_1332
	s_branch .LBB0_1333
	s_nop 0
	s_nop 0
	s_nop 0
	s_nop 0
	s_nop 0
	s_nop 0
	s_nop 0
	s_nop 0
	s_nop 0
	s_nop 0
	s_nop 0
	s_nop 0
	s_nop 0
	s_nop 0
	s_nop 0
	s_nop 0
	s_nop 0
	s_nop 0
	s_nop 0
	s_nop 0
	s_nop 0
	s_nop 0
	s_nop 0
	s_nop 0
	s_nop 0
	s_nop 0
	s_nop 0
	s_nop 0
	s_nop 0
	s_nop 0
	s_nop 0
	s_nop 0
	s_nop 0
	s_nop 0
	s_nop 0
	s_nop 0
	s_nop 0
	s_nop 0
	s_nop 0
	s_nop 0
	s_nop 0
	s_nop 0
	s_nop 0
	s_nop 0
	s_nop 0
	s_nop 0
	s_nop 0
	s_nop 0
	s_nop 0
	s_nop 0
	s_nop 0
	s_nop 0
	s_nop 0
	s_nop 0
	s_nop 0
	s_nop 0
	s_nop 0
	s_nop 0
	s_nop 0
	s_nop 0
	s_nop 0
	s_nop 0
	s_nop 0
	s_nop 0
	s_nop 0
	s_nop 0
	s_nop 0
	s_nop 0
	s_nop 0
	s_nop 0
	s_nop 0
	s_nop 0
	s_nop 0
	s_nop 0
	s_nop 0
	s_nop 0
	s_nop 0
	s_nop 0
	s_nop 0
	s_nop 0
	s_nop 0
	s_nop 0
	s_nop 0
	s_nop 0
	s_nop 0
	s_nop 0
	s_nop 0
	s_nop 0
	s_nop 0
	s_nop 0
	s_nop 0
	s_nop 0
	s_nop 0
	s_nop 0
	s_nop 0
	s_nop 0
	s_nop 0
	s_nop 0
	s_nop 0
	s_nop 0
	s_nop 0
	s_nop 0
	s_nop 0
	s_nop 0

; #define PG8_STAGE(bufoff, gbase, voff) do { _Pragma("unroll") for (int _i = 0; _i < 2; ++_i) \
;         __builtin_amdgcn_global_load_lds((const unsigned*)((const char*)(gbase) + (voff)[_i]), (PG8_LAS unsigned*)(lds + (bufoff) + ldsw + _i * 8192), 16, 0, 0); } while (0)
; #define PG8_LDA(dst, b, h) do { _Pragma("unroll") for (int m = 0; m < 4; ++m) _Pragma("unroll") for (int k = 0; k < 2; ++k) dst[m][k] = *(const PG8_LAS bf16x8*)(lds + PG8_SA(b, h) + aoff + m * 2048 + k * 1024); } while (0)
; #define PG8_LDB(dst, b, h) do { _Pragma("unroll") for (int n = 0; n < 2; ++n) _Pragma("unroll") for (int k = 0; k < 2; ++k) dst[n][k] = *(const PG8_LAS bf16x8*)(lds + PG8_SB(b, h) + boff + n * 2048 + k * 1024); } while (0)
; #define PG8_WAIT_V(n) asm volatile("s_waitcnt vmcnt(" #n ")" ::: "memory")
; template <class Epi, class Sched, bool ALIGN_EPI = false, bool SP2 = false>
; __device__ __forceinline__ void gemm_phase(PG8_LAS unsigned char* lds, const Gemm g, const Sched& S, const Epi& E) {
;     ...
;         const bool has_next = S.next(ui + 1, nxt);
;         const char* nA = has_next ? (const char*)g.A + (size_t)nxt.pm * tstep + (size_t)nxt.kt0 * kstep : cA; const char* nB = has_next ? (const char*)g.Bt + (size_t)nxt.pn * tstep + (size_t)nxt.kt0 * kstep : cB;
;         const int nt = cur.nkt;
;         for (int t = 0; t < nt; t += 2) {
;             const bool last = (t == nt - 2);
;             const char* a1 = cA + (size_t)(t + 1) * kstep;
;             const char* a2 = last ? nA : cA + (size_t)(t + 2) * kstep; const char* b2 = last ? nB : cB + (size_t)(t + 2) * kstep;
;             const char* a3 = a2 + kstep; const char* b3 = b2 + kstep;
;             if (last && has_next) S.a_ready(nxt);
;             if constexpr (SP2) {
;             PG8_LDB(B0, 0, 0); PG8_LDB(B1, 0, 1); PG8_SCHED; PG8_LDA(At, 0, 0); PG8_STAGE(PG8_SA(1, 1), a1 + hstep, voffA);
;             PG8_WAIT_V(8); PG8_WAIT_L(0); PG8_BAR; PG8_MMA(0, 0, At, B0); PG8_MMA(0, 1, At, B1); PG8_BAR; PG8_SCHED;
;     ...
;         if (cur.ks != -2) {
; #pragma unroll
;         for (int a = 0; a < 2; ++a)
; #pragma unroll
;             for (int b = 0; b < 2; ++b)
; #pragma unroll
;                 for (int m = 0; m < 4; ++m)
; #pragma unroll
;                     for (int n = 0; n < 2; ++n) acc[a][b][m][n] = (f32x4){0.f, 0.f, 0.f, 0.f};
;         }
;         cur = nxt; cA = nA; cB = nB; ++ui;
.LBB0_1486:
	s_ashr_i32 s21, s20, 31
	s_lshl_b64 s[2:3], s[20:21], 20
	s_add_u32 s42, s6, s2
	s_addc_u32 s43, s7, s3
	s_and_b64 s[2:3], s[40:41], exec
	s_cselect_b32 s21, s43, s49
	s_cselect_b32 s24, s42, s48
	s_ashr_i32 s19, s18, 31
	s_lshl_b64 s[2:3], s[18:19], 20
	s_add_u32 s44, s10, s2
	s_addc_u32 s45, s11, s3
	s_and_b64 s[2:3], s[40:41], exec
	s_cselect_b32 s19, s45, s23
	s_cselect_b32 s25, s44, s22
	s_add_u32 s55, s22, 0x100
	s_addc_u32 s56, s23, 0
	s_add_u32 s48, s48, 0x80080
	v_mov_b32_e32 v2, 0
	s_addc_u32 s49, s49, 0
	s_mov_b32 s57, -2
	v_mov_b32_e32 v3, v2
	v_mov_b32_e32 v4, v2
	v_mov_b32_e32 v5, v2
	v_mov_b32_e32 v10, v2
	v_mov_b32_e32 v11, v2
	v_mov_b32_e32 v12, v2
	v_mov_b32_e32 v13, v2
	v_mov_b32_e32 v18, v2
	v_mov_b32_e32 v19, v2
	v_mov_b32_e32 v20, v2
	v_mov_b32_e32 v21, v2
	v_mov_b32_e32 v26, v2
	v_mov_b32_e32 v27, v2
	v_mov_b32_e32 v28, v2
	v_mov_b32_e32 v29, v2
	s_waitcnt vmcnt(0)
	v_mov_b32_e32 v34, v2
	v_mov_b32_e32 v35, v2
	v_mov_b32_e32 v36, v2
	v_mov_b32_e32 v37, v2
	v_mov_b32_e32 v42, v2
	v_mov_b32_e32 v43, v2
	v_mov_b32_e32 v44, v2
	v_mov_b32_e32 v45, v2
	v_mov_b32_e32 v50, v2
	v_mov_b32_e32 v51, v2
	v_mov_b32_e32 v52, v2
	v_mov_b32_e32 v53, v2
	v_mov_b32_e32 v58, v2
	v_mov_b32_e32 v59, v2
	v_mov_b32_e32 v60, v2
	v_mov_b32_e32 v61, v2
	v_mov_b32_e32 v6, v2
	v_mov_b32_e32 v7, v2
	v_mov_b32_e32 v8, v2
	v_mov_b32_e32 v9, v2
	v_mov_b32_e32 v14, v2
	v_mov_b32_e32 v15, v2
	v_mov_b32_e32 v16, v2
	v_mov_b32_e32 v17, v2
	v_mov_b32_e32 v22, v2
	v_mov_b32_e32 v23, v2
	v_mov_b32_e32 v24, v2
	v_mov_b32_e32 v25, v2
	v_mov_b32_e32 v30, v2
	v_mov_b32_e32 v31, v2
	v_mov_b32_e32 v32, v2
	v_mov_b32_e32 v33, v2
	v_mov_b32_e32 v38, v2
	v_mov_b32_e32 v39, v2
	v_mov_b32_e32 v40, v2
	v_mov_b32_e32 v41, v2
	v_mov_b32_e32 v46, v2
	v_mov_b32_e32 v47, v2
	v_mov_b32_e32 v48, v2
	v_mov_b32_e32 v49, v2
	v_mov_b32_e32 v54, v2
	v_mov_b32_e32 v55, v2
	v_mov_b32_e32 v56, v2
	v_mov_b32_e32 v57, v2
	v_mov_b32_e32 v62, v2
	v_mov_b32_e32 v63, v2
	v_mov_b32_e32 v64, v2
	v_mov_b32_e32 v65, v2
	v_mov_b32_e32 v66, v2
	v_mov_b32_e32 v67, v2
	v_mov_b32_e32 v68, v2
	v_mov_b32_e32 v69, v2
	v_mov_b32_e32 v74, v2
	v_mov_b32_e32 v75, v2
	v_mov_b32_e32 v76, v2
	v_mov_b32_e32 v77, v2
	v_mov_b32_e32 v82, v2
	v_mov_b32_e32 v83, v2
	v_mov_b32_e32 v84, v2
	v_mov_b32_e32 v85, v2
	v_mov_b32_e32 v90, v2
	v_mov_b32_e32 v91, v2
	v_mov_b32_e32 v92, v2
	v_mov_b32_e32 v93, v2
	v_mov_b32_e32 v98, v2
	v_mov_b32_e32 v99, v2
	v_mov_b32_e32 v100, v2
	v_mov_b32_e32 v101, v2
	v_mov_b32_e32 v106, v2
	v_mov_b32_e32 v107, v2
	v_mov_b32_e32 v108, v2
	v_mov_b32_e32 v109, v2
	v_mov_b32_e32 v114, v2
	v_mov_b32_e32 v115, v2
	v_mov_b32_e32 v116, v2
	v_mov_b32_e32 v117, v2
	v_mov_b32_e32 v122, v2
	v_mov_b32_e32 v123, v2
	v_mov_b32_e32 v124, v2
	v_mov_b32_e32 v125, v2
	v_mov_b32_e32 v70, v2
	v_mov_b32_e32 v71, v2
	v_mov_b32_e32 v72, v2
	v_mov_b32_e32 v73, v2
	v_mov_b32_e32 v78, v2
	v_mov_b32_e32 v79, v2
	v_mov_b32_e32 v80, v2
	v_mov_b32_e32 v81, v2
	v_mov_b32_e32 v86, v2
	v_mov_b32_e32 v87, v2
	v_mov_b32_e32 v88, v2
	v_mov_b32_e32 v89, v2
	v_mov_b32_e32 v94, v2
	v_mov_b32_e32 v95, v2
	v_mov_b32_e32 v96, v2
	v_mov_b32_e32 v97, v2
	v_mov_b32_e32 v102, v2
	v_mov_b32_e32 v103, v2
	v_mov_b32_e32 v104, v2
	v_mov_b32_e32 v105, v2
	v_mov_b32_e32 v110, v2
	v_mov_b32_e32 v111, v2
	v_mov_b32_e32 v112, v2
	v_mov_b32_e32 v113, v2
	v_mov_b32_e32 v118, v2
	v_mov_b32_e32 v119, v2
	v_mov_b32_e32 v120, v2
	v_mov_b32_e32 v121, v2
	v_mov_b32_e32 v126, v2
	v_mov_b32_e32 v127, v2
	v_mov_b32_e32 v128, v2
	v_mov_b32_e32 v129, v2
	s_cmp_eq_u32 s16, 0
	s_cbranch_scc0 .Lmy_p7_prio_done
	s_setprio 1
.Lmy_p7_prio_done:
.LBB0_1487:
	s_add_u32 s2, s48, 0xfff80080
	s_addc_u32 s3, s49, -1
	s_add_i32 s58, 0, 0x10000
	s_cmp_eq_u32 s57, 28
	s_cselect_b32 s51, s21, s3
	s_cselect_b32 s50, s24, s2
	s_cselect_b32 s23, s19, s56
	s_cselect_b32 s22, s25, s55
	s_add_i32 s59, 0, 0x14000
	v_add_u32_e32 v156, s58, v149
	v_add_u32_e32 v172, s59, v149
	ds_read_b128 v[140:143], v156
	ds_read_b128 v[144:147], v156 offset:1024
	ds_read_b128 v[152:155], v156 offset:2048
	ds_read_b128 v[156:159], v156 offset:3072
	ds_read_b128 v[160:163], v172
	ds_read_b128 v[164:167], v172 offset:1024
	ds_read_b128 v[168:171], v172 offset:2048
	ds_read_b128 v[172:175], v172 offset:3072
	v_lshl_add_u64 v[184:185], s[48:49], 0, v[138:139]
	s_add_i32 m0, s35, 0xc000
	ds_read_b128 v[176:179], v151
	ds_read_b128 v[180:183], v151 offset:1024
	ds_read_b128 v[200:203], v151 offset:2048
	ds_read_b128 v[204:207], v151 offset:3072
	ds_read_b128 v[208:211], v151 offset:4096
	ds_read_b128 v[212:215], v151 offset:5120
	ds_read_b128 v[216:219], v151 offset:6144
	ds_read_b128 v[232:235], v151 offset:7168
	global_load_lds_dwordx4 v[184:185], off
	v_lshl_add_u64 v[184:185], s[48:49], 0, v[136:137]
	s_add_i32 m0, s35, 0xe000
	s_nop 0
	global_load_lds_dwordx4 v[184:185], off
	s_waitcnt vmcnt(8)
	s_waitcnt lgkmcnt(0)
	s_barrier
; #define PG8_STAGE(bufoff, gbase, voff) do { _Pragma("unroll") for (int _i = 0; _i < 2; ++_i) \
;         __builtin_amdgcn_global_load_lds((const unsigned*)((const char*)(gbase) + (voff)[_i]), (PG8_LAS unsigned*)(lds + (bufoff) + ldsw + _i * 8192), 16, 0, 0); } while (0)
; #define PG8_LDA(dst, b, h) do { _Pragma("unroll") for (int m = 0; m < 4; ++m) _Pragma("unroll") for (int k = 0; k < 2; ++k) dst[m][k] = *(const PG8_LAS bf16x8*)(lds + PG8_SA(b, h) + aoff + m * 2048 + k * 1024); } while (0)
; #define PG8_MMA(ai, bj, At, Bt) do { __builtin_amdgcn_s_setprio(1); _Pragma("unroll") for (int m = 0; m < 4; ++m) _Pragma("unroll") for (int n = 0; n < 2; ++n) _Pragma("unroll") for (int k = 0; k < 2; ++k) \
;         acc[ai][bj][m][n] = __builtin_amdgcn_mfma_f32_16x16x32_bf16(Bt[n][k], At[m][k], acc[ai][bj][m][n], 0, 0, 0); __builtin_amdgcn_s_setprio(0); } while (0)
; #define PG8_WAIT_V(n) asm volatile("s_waitcnt vmcnt(" #n ")" ::: "memory")
; #define PG8_WAIT_L(n) asm volatile("s_waitcnt lgkmcnt(" #n ")" ::: "memory")
; #define PG8_BAR __builtin_amdgcn_s_barrier()
; #define PG8_SCHED __builtin_amdgcn_sched_barrier(0)
; template <class Epi, class Sched, bool ALIGN_EPI = false, bool SP2 = false>
; __device__ __forceinline__ void gemm_phase(PG8_LAS unsigned char* lds, const Gemm g, const Sched& S, const Epi& E) {
;     ...
;             PG8_WAIT_V(8); PG8_WAIT_L(0); PG8_BAR; PG8_MMA(0, 0, At, B0); PG8_MMA(0, 1, At, B1); PG8_BAR; PG8_SCHED;
;             PG8_LDA(At, 0, 1); PG8_STAGE(PG8_SB(0, 0), b2, voffB); PG8_STAGE(PG8_SB(0, 1), b2 + hstep, voffB); PG8_STAGE(PG8_SA(0, 0), a2, voffA);
;             PG8_WAIT_V(8); PG8_WAIT_L(0); PG8_BAR; PG8_MMA(1, 0, At, B0); PG8_MMA(1, 1, At, B1); PG8_BAR; PG8_SCHED;
	s_nop 0
	s_waitcnt lgkmcnt(0)
	v_mfma_f32_16x16x32_bf16 v[126:129], v[140:143], v[176:179], v[126:129]
	v_mfma_f32_16x16x32_bf16 v[118:121], v[152:155], v[176:179], v[118:121]
	v_mfma_f32_16x16x32_bf16 v[110:113], v[140:143], v[200:203], v[110:113]
	v_mfma_f32_16x16x32_bf16 v[102:105], v[152:155], v[200:203], v[102:105]
	v_mfma_f32_16x16x32_bf16 v[94:97], v[140:143], v[208:211], v[94:97]
	v_mfma_f32_16x16x32_bf16 v[86:89], v[152:155], v[208:211], v[86:89]
	v_mfma_f32_16x16x32_bf16 v[78:81], v[140:143], v[216:219], v[78:81]
	v_mfma_f32_16x16x32_bf16 v[70:73], v[152:155], v[216:219], v[70:73]
	v_mfma_f32_16x16x32_bf16 v[126:129], v[144:147], v[180:183], v[126:129]
	v_mfma_f32_16x16x32_bf16 v[118:121], v[156:159], v[180:183], v[118:121]
	v_mfma_f32_16x16x32_bf16 v[110:113], v[144:147], v[204:207], v[110:113]
	v_mfma_f32_16x16x32_bf16 v[102:105], v[156:159], v[204:207], v[102:105]
	v_mfma_f32_16x16x32_bf16 v[94:97], v[144:147], v[212:215], v[94:97]
	v_mfma_f32_16x16x32_bf16 v[86:89], v[156:159], v[212:215], v[86:89]
	v_mfma_f32_16x16x32_bf16 v[78:81], v[144:147], v[232:235], v[78:81]
	v_mfma_f32_16x16x32_bf16 v[70:73], v[156:159], v[232:235], v[70:73]
	s_nop 0
	s_nop 0
	v_mfma_f32_16x16x32_bf16 v[122:125], v[160:163], v[176:179], v[122:125]
	v_mfma_f32_16x16x32_bf16 v[114:117], v[168:171], v[176:179], v[114:117]
	v_mfma_f32_16x16x32_bf16 v[106:109], v[160:163], v[200:203], v[106:109]
	v_mfma_f32_16x16x32_bf16 v[98:101], v[168:171], v[200:203], v[98:101]
	v_mfma_f32_16x16x32_bf16 v[90:93], v[160:163], v[208:211], v[90:93]
	v_mfma_f32_16x16x32_bf16 v[82:85], v[168:171], v[208:211], v[82:85]
	v_mfma_f32_16x16x32_bf16 v[74:77], v[160:163], v[216:219], v[74:77]
	v_mfma_f32_16x16x32_bf16 v[66:69], v[168:171], v[216:219], v[66:69]
	v_mfma_f32_16x16x32_bf16 v[122:125], v[164:167], v[180:183], v[122:125]
	v_mfma_f32_16x16x32_bf16 v[114:117], v[172:175], v[180:183], v[114:117]
	v_mfma_f32_16x16x32_bf16 v[106:109], v[164:167], v[204:207], v[106:109]
	v_mfma_f32_16x16x32_bf16 v[98:101], v[172:175], v[204:207], v[98:101]
	v_mfma_f32_16x16x32_bf16 v[90:93], v[164:167], v[212:215], v[90:93]
	v_mfma_f32_16x16x32_bf16 v[82:85], v[172:175], v[212:215], v[82:85]
	v_mfma_f32_16x16x32_bf16 v[74:77], v[164:167], v[232:235], v[74:77]
	v_mfma_f32_16x16x32_bf16 v[66:69], v[172:175], v[232:235], v[66:69]
	s_nop 0
	s_barrier
	s_add_i32 s2, s58, s28
	v_lshl_add_u64 v[184:185], s[22:23], 0, v[0:1]
	s_mov_b32 m0, s2
	ds_read_b128 v[176:179], v151 offset:16384
	ds_read_b128 v[180:183], v151 offset:17408
	ds_read_b128 v[200:203], v151 offset:18432
	ds_read_b128 v[204:207], v151 offset:19456
	ds_read_b128 v[208:211], v151 offset:20480
	ds_read_b128 v[212:215], v151 offset:21504
	ds_read_b128 v[216:219], v151 offset:22528
	ds_read_b128 v[232:235], v151 offset:23552
	global_load_lds_dwordx4 v[184:185], off
	s_add_i32 m0, s2, 0x2000
	s_add_u32 s2, s22, 0x80000
	v_lshl_add_u64 v[236:237], s[22:23], 0, v[130:131]
	s_addc_u32 s3, s23, 0
	s_add_i32 s58, s59, s28
	global_load_lds_dwordx4 v[236:237], off
	v_lshl_add_u64 v[238:239], s[2:3], 0, v[0:1]
	s_mov_b32 m0, s58
	v_lshl_add_u64 v[240:241], s[50:51], 0, v[132:133]
	global_load_lds_dwordx4 v[238:239], off
	v_lshl_add_u64 v[238:239], s[2:3], 0, v[130:131]
	s_add_i32 m0, s58, 0x2000
	s_nop 0
	global_load_lds_dwordx4 v[238:239], off
	v_lshl_add_u64 v[238:239], s[50:51], 0, v[134:135]
	s_mov_b32 m0, s35
	s_nop 0
	global_load_lds_dwordx4 v[238:239], off
	s_mov_b32 m0, s36
	s_nop 0
	global_load_lds_dwordx4 v[240:241], off
	s_waitcnt vmcnt(8)
	s_waitcnt lgkmcnt(0)
	s_barrier
	s_nop 0
	s_waitcnt lgkmcnt(0)
	v_mfma_f32_16x16x32_bf16 v[62:65], v[140:143], v[176:179], v[62:65]
	v_mfma_f32_16x16x32_bf16 v[54:57], v[152:155], v[176:179], v[54:57]
	v_mfma_f32_16x16x32_bf16 v[46:49], v[140:143], v[200:203], v[46:49]
	v_mfma_f32_16x16x32_bf16 v[38:41], v[152:155], v[200:203], v[38:41]
	v_mfma_f32_16x16x32_bf16 v[30:33], v[140:143], v[208:211], v[30:33]
	v_mfma_f32_16x16x32_bf16 v[22:25], v[152:155], v[208:211], v[22:25]
	v_mfma_f32_16x16x32_bf16 v[14:17], v[140:143], v[216:219], v[14:17]
	v_mfma_f32_16x16x32_bf16 v[6:9], v[152:155], v[216:219], v[6:9]
	v_mfma_f32_16x16x32_bf16 v[62:65], v[144:147], v[180:183], v[62:65]
	v_mfma_f32_16x16x32_bf16 v[54:57], v[156:159], v[180:183], v[54:57]
	v_mfma_f32_16x16x32_bf16 v[46:49], v[144:147], v[204:207], v[46:49]
	v_mfma_f32_16x16x32_bf16 v[38:41], v[156:159], v[204:207], v[38:41]
	v_mfma_f32_16x16x32_bf16 v[30:33], v[144:147], v[212:215], v[30:33]
	v_mfma_f32_16x16x32_bf16 v[22:25], v[156:159], v[212:215], v[22:25]
	v_mfma_f32_16x16x32_bf16 v[14:17], v[144:147], v[232:235], v[14:17]
	v_mfma_f32_16x16x32_bf16 v[6:9], v[156:159], v[232:235], v[6:9]
	s_nop 0
	s_nop 0
	v_mfma_f32_16x16x32_bf16 v[58:61], v[160:163], v[176:179], v[58:61]
	v_mfma_f32_16x16x32_bf16 v[50:53], v[168:171], v[176:179], v[50:53]
	v_mfma_f32_16x16x32_bf16 v[42:45], v[160:163], v[200:203], v[42:45]
	v_mfma_f32_16x16x32_bf16 v[34:37], v[168:171], v[200:203], v[34:37]
	v_mfma_f32_16x16x32_bf16 v[26:29], v[160:163], v[208:211], v[26:29]
	v_mfma_f32_16x16x32_bf16 v[18:21], v[168:171], v[208:211], v[18:21]
	v_mfma_f32_16x16x32_bf16 v[10:13], v[160:163], v[216:219], v[10:13]
	v_mfma_f32_16x16x32_bf16 v[2:5], v[168:171], v[216:219], v[2:5]
	v_mfma_f32_16x16x32_bf16 v[58:61], v[164:167], v[180:183], v[58:61]
	v_mfma_f32_16x16x32_bf16 v[50:53], v[172:175], v[180:183], v[50:53]
	v_mfma_f32_16x16x32_bf16 v[42:45], v[164:167], v[204:207], v[42:45]
	v_mfma_f32_16x16x32_bf16 v[34:37], v[172:175], v[204:207], v[34:37]
	v_mfma_f32_16x16x32_bf16 v[26:29], v[164:167], v[212:215], v[26:29]
	v_mfma_f32_16x16x32_bf16 v[18:21], v[172:175], v[212:215], v[18:21]
	v_mfma_f32_16x16x32_bf16 v[10:13], v[164:167], v[232:235], v[10:13]
	v_mfma_f32_16x16x32_bf16 v[2:5], v[172:175], v[232:235], v[2:5]
	s_nop 0
	s_barrier
; #define PG8_STAGE(bufoff, gbase, voff) do { _Pragma("unroll") for (int _i = 0; _i < 2; ++_i) \
;         __builtin_amdgcn_global_load_lds((const unsigned*)((const char*)(gbase) + (voff)[_i]), (PG8_LAS unsigned*)(lds + (bufoff) + ldsw + _i * 8192), 16, 0, 0); } while (0)
; #define PG8_LDA(dst, b, h) do { _Pragma("unroll") for (int m = 0; m < 4; ++m) _Pragma("unroll") for (int k = 0; k < 2; ++k) dst[m][k] = *(const PG8_LAS bf16x8*)(lds + PG8_SA(b, h) + aoff + m * 2048 + k * 1024); } while (0)
; #define PG8_LDB(dst, b, h) do { _Pragma("unroll") for (int n = 0; n < 2; ++n) _Pragma("unroll") for (int k = 0; k < 2; ++k) dst[n][k] = *(const PG8_LAS bf16x8*)(lds + PG8_SB(b, h) + boff + n * 2048 + k * 1024); } while (0)
; #define PG8_MMA(ai, bj, At, Bt) do { __builtin_amdgcn_s_setprio(1); _Pragma("unroll") for (int m = 0; m < 4; ++m) _Pragma("unroll") for (int n = 0; n < 2; ++n) _Pragma("unroll") for (int k = 0; k < 2; ++k) \
;         acc[ai][bj][m][n] = __builtin_amdgcn_mfma_f32_16x16x32_bf16(Bt[n][k], At[m][k], acc[ai][bj][m][n], 0, 0, 0); __builtin_amdgcn_s_setprio(0); } while (0)
; #define PG8_WAIT_V(n) asm volatile("s_waitcnt vmcnt(" #n ")" ::: "memory")
; #define PG8_WAIT_L(n) asm volatile("s_waitcnt lgkmcnt(" #n ")" ::: "memory")
; #define PG8_BAR __builtin_amdgcn_s_barrier()
; #define PG8_SCHED __builtin_amdgcn_sched_barrier(0)
; template <class Epi, class Sched, bool ALIGN_EPI = false, bool SP2 = false>
; __device__ __forceinline__ void gemm_phase(PG8_LAS unsigned char* lds, const Gemm g, const Sched& S, const Epi& E) {
;     ...
;             PG8_LDB(B0, 1, 0); PG8_LDB(B1, 1, 1); PG8_SCHED; PG8_LDA(At, 1, 0); PG8_STAGE(PG8_SA(0, 1), a2 + hstep, voffA);
;             PG8_WAIT_V(8); PG8_WAIT_L(0); PG8_BAR; PG8_MMA(0, 0, At, B0); PG8_MMA(0, 1, At, B1); PG8_BAR; PG8_SCHED;
;             PG8_LDA(At, 1, 1); PG8_STAGE(PG8_SB(1, 0), b3, voffB); PG8_STAGE(PG8_SB(1, 1), b3 + hstep, voffB); PG8_STAGE(PG8_SA(1, 0), a3, voffA);
;             PG8_WAIT_V(8); PG8_WAIT_L(0); PG8_BAR; PG8_MMA(1, 0, At, B0); PG8_MMA(1, 1, At, B1); PG8_BAR; PG8_SCHED;
	s_add_i32 s58, 0, 0x18000
	s_add_i32 s59, 0, 0x1c000
	v_add_u32_e32 v156, s58, v149
	v_add_u32_e32 v172, s59, v149
	ds_read_b128 v[140:143], v156
	ds_read_b128 v[144:147], v156 offset:1024
	ds_read_b128 v[152:155], v156 offset:2048
	ds_read_b128 v[156:159], v156 offset:3072
	ds_read_b128 v[160:163], v172
	ds_read_b128 v[164:167], v172 offset:1024
	ds_read_b128 v[168:171], v172 offset:2048
	ds_read_b128 v[172:175], v172 offset:3072
	s_add_u32 s2, s50, 0x80000
	s_addc_u32 s3, s51, 0
	s_mov_b32 m0, s37
	v_lshl_add_u64 v[242:243], s[2:3], 0, v[134:135]
	ds_read_b128 v[176:179], v151 offset:32768
	ds_read_b128 v[180:183], v151 offset:33792
	ds_read_b128 v[200:203], v151 offset:34816
	ds_read_b128 v[204:207], v151 offset:35840
	ds_read_b128 v[208:211], v151 offset:36864
	ds_read_b128 v[212:215], v151 offset:37888
	ds_read_b128 v[216:219], v151 offset:38912
	ds_read_b128 v[232:235], v151 offset:39936
	global_load_lds_dwordx4 v[242:243], off
	v_lshl_add_u64 v[242:243], s[2:3], 0, v[132:133]
	s_mov_b32 m0, s38
	s_nop 0
	global_load_lds_dwordx4 v[242:243], off
	s_waitcnt vmcnt(8)
	s_waitcnt lgkmcnt(0)
	s_barrier
	s_nop 0
	s_waitcnt lgkmcnt(0)
	v_mfma_f32_16x16x32_bf16 v[126:129], v[140:143], v[176:179], v[126:129]
	v_mfma_f32_16x16x32_bf16 v[118:121], v[152:155], v[176:179], v[118:121]
	v_mfma_f32_16x16x32_bf16 v[110:113], v[140:143], v[200:203], v[110:113]
	v_mfma_f32_16x16x32_bf16 v[102:105], v[152:155], v[200:203], v[102:105]
	v_mfma_f32_16x16x32_bf16 v[94:97], v[140:143], v[208:211], v[94:97]
	v_mfma_f32_16x16x32_bf16 v[86:89], v[152:155], v[208:211], v[86:89]
	v_mfma_f32_16x16x32_bf16 v[78:81], v[140:143], v[216:219], v[78:81]
	v_mfma_f32_16x16x32_bf16 v[70:73], v[152:155], v[216:219], v[70:73]
	v_mfma_f32_16x16x32_bf16 v[126:129], v[144:147], v[180:183], v[126:129]
	v_mfma_f32_16x16x32_bf16 v[118:121], v[156:159], v[180:183], v[118:121]
	v_mfma_f32_16x16x32_bf16 v[110:113], v[144:147], v[204:207], v[110:113]
	v_mfma_f32_16x16x32_bf16 v[102:105], v[156:159], v[204:207], v[102:105]
	v_mfma_f32_16x16x32_bf16 v[94:97], v[144:147], v[212:215], v[94:97]
	v_mfma_f32_16x16x32_bf16 v[86:89], v[156:159], v[212:215], v[86:89]
	v_mfma_f32_16x16x32_bf16 v[78:81], v[144:147], v[232:235], v[78:81]
	v_mfma_f32_16x16x32_bf16 v[70:73], v[156:159], v[232:235], v[70:73]
	s_nop 0
	s_nop 0
	v_mfma_f32_16x16x32_bf16 v[122:125], v[160:163], v[176:179], v[122:125]
	v_mfma_f32_16x16x32_bf16 v[114:117], v[168:171], v[176:179], v[114:117]
	v_mfma_f32_16x16x32_bf16 v[106:109], v[160:163], v[200:203], v[106:109]
	v_mfma_f32_16x16x32_bf16 v[98:101], v[168:171], v[200:203], v[98:101]
	v_mfma_f32_16x16x32_bf16 v[90:93], v[160:163], v[208:211], v[90:93]
	v_mfma_f32_16x16x32_bf16 v[82:85], v[168:171], v[208:211], v[82:85]
	v_mfma_f32_16x16x32_bf16 v[74:77], v[160:163], v[216:219], v[74:77]
	v_mfma_f32_16x16x32_bf16 v[66:69], v[168:171], v[216:219], v[66:69]
	v_mfma_f32_16x16x32_bf16 v[122:125], v[164:167], v[180:183], v[122:125]
	v_mfma_f32_16x16x32_bf16 v[114:117], v[172:175], v[180:183], v[114:117]
	v_mfma_f32_16x16x32_bf16 v[106:109], v[164:167], v[204:207], v[106:109]
	v_mfma_f32_16x16x32_bf16 v[98:101], v[172:175], v[204:207], v[98:101]
	v_mfma_f32_16x16x32_bf16 v[90:93], v[164:167], v[212:215], v[90:93]
	v_mfma_f32_16x16x32_bf16 v[82:85], v[172:175], v[212:215], v[82:85]
	v_mfma_f32_16x16x32_bf16 v[74:77], v[164:167], v[232:235], v[74:77]
	v_mfma_f32_16x16x32_bf16 v[66:69], v[172:175], v[232:235], v[66:69]
	s_nop 0
	s_barrier
	s_add_i32 s2, s58, s28
	v_lshl_add_u64 v[184:185], v[184:185], 0, s[0:1]
	s_mov_b32 m0, s2
	ds_read_b128 v[176:179], v151 offset:49152
	ds_read_b128 v[180:183], v151 offset:50176
	ds_read_b128 v[200:203], v151 offset:51200
	ds_read_b128 v[204:207], v151 offset:52224
	ds_read_b128 v[208:211], v151 offset:53248
	ds_read_b128 v[212:215], v151 offset:54272
	ds_read_b128 v[216:219], v151 offset:55296
	ds_read_b128 v[232:235], v151 offset:56320
	global_load_lds_dwordx4 v[184:185], off
	s_add_i32 m0, s2, 0x2000
	s_add_u32 s2, s22, 0x80080
	v_lshl_add_u64 v[184:185], v[236:237], 0, s[0:1]
	s_addc_u32 s3, s23, 0
	s_add_i32 s22, s59, s28
	global_load_lds_dwordx4 v[184:185], off
	v_lshl_add_u64 v[184:185], s[2:3], 0, v[0:1]
	s_mov_b32 m0, s22
	s_nop 0
	global_load_lds_dwordx4 v[184:185], off
	v_lshl_add_u64 v[184:185], s[2:3], 0, v[130:131]
	s_add_i32 m0, s22, 0x2000
	s_nop 0
	global_load_lds_dwordx4 v[184:185], off
	v_lshl_add_u64 v[184:185], v[238:239], 0, s[0:1]
	s_mov_b32 m0, s47
	s_nop 0
	global_load_lds_dwordx4 v[184:185], off
	v_lshl_add_u64 v[184:185], v[240:241], 0, s[0:1]
	s_mov_b32 m0, s52
	s_nop 0
	global_load_lds_dwordx4 v[184:185], off
	s_waitcnt vmcnt(8)
	s_waitcnt lgkmcnt(0)
	s_barrier
; #define PG8_BAR __builtin_amdgcn_s_barrier()
; template <class Epi, class Sched, bool ALIGN_EPI = false, bool SP2 = false>
; __device__ __forceinline__ void gemm_phase(PG8_LAS unsigned char* lds, const Gemm g, const Sched& S, const Epi& E) {
;     ...
;             PG8_WAIT_V(8); PG8_WAIT_L(0); PG8_BAR; PG8_MMA(1, 0, At, B0); PG8_MMA(1, 1, At, B1); PG8_BAR; PG8_SCHED;
;             } else {
;             PG8_LDB(B0, 0, 0); PG8_SCHED; PG8_LDA(At, 0, 0); PG8_STAGE(PG8_SA(1, 1), a1 + hstep, voffA);
;             PG8_WAIT_L(8); PG8_BAR; PG8_WAIT_L(0); PG8_MMA(0, 0, At, B0); PG8_BAR; PG8_SCHED;
;             PG8_LDB(B1, 0, 1); PG8_STAGE(PG8_SB(0, 0), b2, voffB);
;             PG8_BAR; PG8_WAIT_L(0); PG8_MMA(0, 1, At, B1); PG8_BAR;
;             PG8_LDA(At, 0, 1); PG8_STAGE(PG8_SA(0, 0), a2, voffA);
;             PG8_BAR; PG8_WAIT_L(0); PG8_MMA(1, 0, At, B0); PG8_BAR; PG8_SCHED;
;             PG8_STAGE(PG8_SB(0, 1), b2 + hstep, voffB);
;             PG8_WAIT_V(6); PG8_BAR; PG8_MMA(1, 1, At, B1); PG8_BAR;
;             PG8_LDB(B0, 1, 0); PG8_SCHED; PG8_LDA(At, 1, 0); PG8_STAGE(PG8_SA(0, 1), a2 + hstep, voffA);
;             PG8_WAIT_L(8); PG8_BAR; PG8_WAIT_L(0); PG8_MMA(0, 0, At, B0); PG8_BAR; PG8_SCHED;
;             PG8_LDB(B1, 1, 1); PG8_STAGE(PG8_SB(1, 0), b3, voffB);
;             PG8_BAR; PG8_WAIT_L(0); PG8_MMA(0, 1, At, B1); PG8_BAR;
;             PG8_LDA(At, 1, 1); PG8_STAGE(PG8_SA(1, 0), a3, voffA);
;             PG8_BAR; PG8_WAIT_L(0); PG8_MMA(1, 0, At, B0); PG8_BAR; PG8_SCHED;
;             PG8_STAGE(PG8_SB(1, 1), b3 + hstep, voffB);
;             PG8_WAIT_V(6); PG8_BAR; PG8_MMA(1, 1, At, B1); PG8_BAR;
;             }
;         }
;         if constexpr (ALIGN_EPI) { if (wr == 0) PG8_BAR; }
;     __device__ __forceinline__ void operator()(const f32x4 (&acc)[2][2][4][2], const Unit& u, int wr, int wc, int fr, int fq) const {
;         const int row0 = u.pm * BM + wr * 64 + fr, col0 = u.pn * HALF + wc * 32 + 8 * fq;
;         float rs[2][4];
; #pragma unroll
;         for (int ai = 0; ai < 2; ++ai)
; #pragma unroll
;             for (int m = 0; m < 4; ++m) rs[ai][m] = ssq[row0 + ai * HALF + m * 16];
; #pragma unroll
;         for (int ai = 0; ai < 2; ++ai)
; #pragma unroll
;             for (int m = 0; m < 4; ++m) { bf16_t* rowp = O + (size_t)(row0 + ai * HALF + m * 16) * DFF + col0; const float rsv = rsqrtf(rs[ai][m] * (1.f / D) + EPS);
	s_nop 0
	s_waitcnt lgkmcnt(0)
	v_mfma_f32_16x16x32_bf16 v[62:65], v[140:143], v[176:179], v[62:65]
	v_mfma_f32_16x16x32_bf16 v[54:57], v[152:155], v[176:179], v[54:57]
	v_mfma_f32_16x16x32_bf16 v[46:49], v[140:143], v[200:203], v[46:49]
	v_mfma_f32_16x16x32_bf16 v[38:41], v[152:155], v[200:203], v[38:41]
	v_mfma_f32_16x16x32_bf16 v[30:33], v[140:143], v[208:211], v[30:33]
	v_mfma_f32_16x16x32_bf16 v[22:25], v[152:155], v[208:211], v[22:25]
	v_mfma_f32_16x16x32_bf16 v[14:17], v[140:143], v[216:219], v[14:17]
	v_mfma_f32_16x16x32_bf16 v[6:9], v[152:155], v[216:219], v[6:9]
	v_mfma_f32_16x16x32_bf16 v[62:65], v[144:147], v[180:183], v[62:65]
	v_mfma_f32_16x16x32_bf16 v[54:57], v[156:159], v[180:183], v[54:57]
	v_mfma_f32_16x16x32_bf16 v[46:49], v[144:147], v[204:207], v[46:49]
	v_mfma_f32_16x16x32_bf16 v[38:41], v[156:159], v[204:207], v[38:41]
	v_mfma_f32_16x16x32_bf16 v[30:33], v[144:147], v[212:215], v[30:33]
	v_mfma_f32_16x16x32_bf16 v[22:25], v[156:159], v[212:215], v[22:25]
	v_mfma_f32_16x16x32_bf16 v[14:17], v[144:147], v[232:235], v[14:17]
	v_mfma_f32_16x16x32_bf16 v[6:9], v[156:159], v[232:235], v[6:9]
	s_nop 0
	s_nop 0
	v_mfma_f32_16x16x32_bf16 v[58:61], v[160:163], v[176:179], v[58:61]
	v_mfma_f32_16x16x32_bf16 v[50:53], v[168:171], v[176:179], v[50:53]
	v_mfma_f32_16x16x32_bf16 v[42:45], v[160:163], v[200:203], v[42:45]
	v_mfma_f32_16x16x32_bf16 v[34:37], v[168:171], v[200:203], v[34:37]
	v_mfma_f32_16x16x32_bf16 v[26:29], v[160:163], v[208:211], v[26:29]
	v_mfma_f32_16x16x32_bf16 v[18:21], v[168:171], v[208:211], v[18:21]
	v_mfma_f32_16x16x32_bf16 v[10:13], v[160:163], v[216:219], v[10:13]
	v_mfma_f32_16x16x32_bf16 v[2:5], v[168:171], v[216:219], v[2:5]
	v_mfma_f32_16x16x32_bf16 v[58:61], v[164:167], v[180:183], v[58:61]
	v_mfma_f32_16x16x32_bf16 v[50:53], v[172:175], v[180:183], v[50:53]
	v_mfma_f32_16x16x32_bf16 v[42:45], v[164:167], v[204:207], v[42:45]
	v_mfma_f32_16x16x32_bf16 v[34:37], v[172:175], v[204:207], v[34:37]
	v_mfma_f32_16x16x32_bf16 v[26:29], v[164:167], v[212:215], v[26:29]
	v_mfma_f32_16x16x32_bf16 v[18:21], v[172:175], v[212:215], v[18:21]
	v_mfma_f32_16x16x32_bf16 v[10:13], v[164:167], v[232:235], v[10:13]
	v_mfma_f32_16x16x32_bf16 v[2:5], v[172:175], v[232:235], v[2:5]
	s_nop 0
	s_barrier
	s_add_i32 s57, s57, 2
	s_add_u32 s55, s55, 0x100
	s_addc_u32 s56, s56, 0
	s_add_u32 s48, s48, 0x100
	s_addc_u32 s49, s49, 0
	s_cmp_gt_u32 s57, 29
	s_cbranch_scc0 .LBB0_1487
	s_setprio 0
	s_and_b64 vcc, exec, s[16:17]
	s_cbranch_vccz .LBB0_1490
	s_barrier
.LBB0_1490:
	v_lshl_add_u32 v144, s46, 8, v148
	v_ashrrev_i32_e32 v145, 31, v144
	v_lshl_add_u64 v[140:141], v[144:145], 2, s[12:13]
	flat_load_dword v146, v[140:141]
	flat_load_dword v164, v[140:141] offset:64
	flat_load_dword v162, v[140:141] offset:128
	flat_load_dword v160, v[140:141] offset:192
	flat_load_dword v158, v[140:141] offset:512
	flat_load_dword v156, v[140:141] offset:576
	flat_load_dword v154, v[140:141] offset:640
	flat_load_dword v152, v[140:141] offset:704
	v_mov_b32_e32 v166, v126
	v_lshl_or_b32 v142, s54, 7, v150
	v_ashrrev_i32_e32 v143, 31, v142
	v_mov_b64_e32 v[140:141], s[8:9]
	v_or_b32_e32 v165, 16, v144
	v_or_b32_e32 v163, 32, v144
	v_or_b32_e32 v161, 48, v144
	v_add_u32_e32 v159, 0x80, v144
	v_add_u32_e32 v157, 0x90, v144
	v_add_u32_e32 v155, 0xa0, v144
	v_add_u32_e32 v153, 0xb0, v144
	v_mad_i64_i32 v[144:145], s[2:3], v144, s34, v[140:141]
	s_mov_b64 s[22:23], -1
	s_mov_b64 s[56:57], s[94:95]
	s_waitcnt vmcnt(0) lgkmcnt(0)
	v_fmamk_f32 v146, v146, 0x3a000000, v223
	v_cmp_gt_f32_e32 vcc, s29, v146
	v_mul_f32_e32 v147, 0x4b800000, v146
	s_nop 0
	v_cndmask_b32_e32 v146, v146, v147, vcc
	v_rsq_f32_e32 v146, v146
	s_nop 0
	v_mul_f32_e32 v147, 0x45800000, v146
	v_cndmask_b32_e32 v146, v146, v147, vcc
	v_mul_f32_e32 v168, 0xbfb8aa3b, v146
	v_mul_f32_e32 v147, v146, v146
	v_mul_f32_e32 v146, v126, v168
	v_exp_f32_e32 v146, v146
	s_nop 0
	v_add_f32_e32 v146, 1.0, v146
	v_rcp_f32_e32 v167, v146
	v_mov_b32_e32 v146, v122
	v_mul_f32_e32 v122, v127, v168
	v_exp_f32_e32 v122, v122
	v_pk_mul_f32 v[166:167], v[146:147], v[166:167]
	v_mov_b32_e32 v146, v123
	v_mul_f32_e32 v126, v166, v167
	v_add_f32_e32 v122, 1.0, v122
	v_rcp_f32_e32 v167, v122
	v_mov_b32_e32 v166, v127
	v_pk_mul_f32 v[122:123], v[146:147], v[166:167]
	s_nop 0
	v_mul_f32_e32 v127, v122, v123
	v_mul_f32_e32 v122, v128, v168
	v_exp_f32_e32 v122, v122
	v_mov_b32_e32 v146, v124
	v_add_f32_e32 v122, 1.0, v122
	v_rcp_f32_e32 v123, v122
	v_mov_b32_e32 v122, v128
	v_pk_mul_f32 v[122:123], v[146:147], v[122:123]
	s_nop 0
	v_mul_f32_e32 v124, v122, v123
	v_mul_f32_e32 v122, v129, v168
	v_exp_f32_e32 v122, v122
	v_mov_b32_e32 v146, v125
	v_add_f32_e32 v122, 1.0, v122
	v_rcp_f32_e32 v123, v122
	v_mov_b32_e32 v122, v129
	v_pk_mul_f32 v[122:123], v[146:147], v[122:123]
	s_nop 0
	v_mul_f32_e32 v125, v122, v123
	v_mul_f32_e32 v122, v118, v168
	v_exp_f32_e32 v122, v122
	v_mov_b32_e32 v146, v114
	v_mul_f32_e32 v114, v119, v168
	v_exp_f32_e32 v114, v114
	v_add_f32_e32 v122, 1.0, v122
	v_rcp_f32_e32 v123, v122
	v_mov_b32_e32 v122, v118
	v_add_f32_e32 v114, 1.0, v114
	v_pk_mul_f32 v[122:123], v[146:147], v[122:123]
	s_nop 0
	v_mul_f32_e32 v118, v122, v123
	v_rcp_f32_e32 v123, v114
	v_mov_b32_e32 v146, v115
	v_mov_b32_e32 v122, v119
	v_pk_mul_f32 v[114:115], v[146:147], v[122:123]
	s_nop 0
	v_mul_f32_e32 v119, v114, v115
	v_mul_f32_e32 v114, v120, v168
	v_exp_f32_e32 v114, v114
	v_mov_b32_e32 v146, v116
	v_cvt_pk_bf16_f32 v116, v126, v127
	v_add_f32_e32 v114, 1.0, v114
	v_rcp_f32_e32 v115, v114
	v_mov_b32_e32 v114, v120
	v_pk_mul_f32 v[114:115], v[146:147], v[114:115]
	s_nop 0
	v_mul_f32_e32 v122, v114, v115
; __device__ __forceinline__ unsigned pk2(float lo, float hi) { unsigned r; asm volatile("v_cvt_pk_bf16_f32 %0, %1, %2" : "=v"(r) : "v"(lo), "v"(hi)); return r; }
;     __device__ __forceinline__ void operator()(const f32x4 (&acc)[2][2][4][2], const Unit& u, int wr, int wc, int fr, int fq) const {
;     ...
; #pragma unroll
;         for (int ai = 0; ai < 2; ++ai)
; #pragma unroll
;             for (int m = 0; m < 4; ++m) { bf16_t* rowp = O + (size_t)(row0 + ai * HALF + m * 16) * DFF + col0; const float rsv = rsqrtf(rs[ai][m] * (1.f / D) + EPS);
;                 const float rs2 = rsv * rsv, nrs = -1.4426950409f * rsv;
;                 float v[8];
; #pragma unroll
;                 for (int n = 0; n < 2; ++n)
; #pragma unroll
;                     for (int j = 0; j < 4; ++j) {
;                         const float g0 = acc[ai][0][m][n][j], u0 = acc[ai][1][m][n][j];
;                         v[n * 4 + j] = (g0 * u0) * (rs2 * __builtin_amdgcn_rcpf(1.0f + __builtin_amdgcn_exp2f(g0 * nrs))); }
;                 u32x4 w; w.x = pk2(v[0], v[1]); w.y = pk2(v[2], v[3]); w.z = pk2(v[4], v[5]); w.w = pk2(v[6], v[7]);
;                 *(u32x4*)rowp = w; }
	v_mul_f32_e32 v114, v121, v168
	v_exp_f32_e32 v114, v114
	v_mov_b32_e32 v146, v117
	v_cvt_pk_bf16_f32 v117, v124, v125
	v_cvt_pk_bf16_f32 v118, v118, v119
	v_add_f32_e32 v114, 1.0, v114
	v_rcp_f32_e32 v115, v114
	v_mov_b32_e32 v114, v121
	v_pk_mul_f32 v[114:115], v[146:147], v[114:115]
	s_nop 0
	v_mul_f32_e32 v123, v114, v115
	v_lshlrev_b64 v[114:115], 1, v[142:143]
	v_lshl_add_u64 v[120:121], v[144:145], 0, v[114:115]
	v_cvt_pk_bf16_f32 v119, v122, v123
	flat_store_dwordx4 v[120:121], v[116:119]
	v_mov_b32_e32 v120, v110
	s_nop 0
	v_fmamk_f32 v118, v164, 0x3a000000, v223
	v_cmp_gt_f32_e32 vcc, s29, v118
	v_mul_f32_e32 v119, 0x4b800000, v118
	v_mad_i64_i32 v[116:117], s[2:3], v165, s34, v[140:141]
	v_cndmask_b32_e32 v118, v118, v119, vcc
	v_rsq_f32_e32 v118, v118
	s_nop 0
	v_mul_f32_e32 v119, 0x45800000, v118
	v_cndmask_b32_e32 v118, v118, v119, vcc
	v_mul_f32_e32 v122, 0xbfb8aa3b, v118
	v_mul_f32_e32 v119, v118, v118
	v_mul_f32_e32 v118, v110, v122
	v_exp_f32_e32 v118, v118
	s_nop 0
	v_add_f32_e32 v118, 1.0, v118
	v_rcp_f32_e32 v121, v118
	v_mov_b32_e32 v118, v106
	v_mul_f32_e32 v106, v111, v122
	v_exp_f32_e32 v106, v106
	v_pk_mul_f32 v[120:121], v[118:119], v[120:121]
	v_mov_b32_e32 v118, v107
	v_mul_f32_e32 v110, v120, v121
	v_add_f32_e32 v106, 1.0, v106
	v_rcp_f32_e32 v121, v106
	v_mov_b32_e32 v120, v111
	v_pk_mul_f32 v[106:107], v[118:119], v[120:121]
	s_nop 0
	v_mul_f32_e32 v111, v106, v107
	v_mul_f32_e32 v106, v112, v122
	v_exp_f32_e32 v106, v106
	v_mov_b32_e32 v118, v108
	v_add_f32_e32 v106, 1.0, v106
	v_rcp_f32_e32 v107, v106
	v_mov_b32_e32 v106, v112
	v_pk_mul_f32 v[106:107], v[118:119], v[106:107]
	s_nop 0
	v_mul_f32_e32 v108, v106, v107
	v_mul_f32_e32 v106, v113, v122
	v_exp_f32_e32 v106, v106
	v_mov_b32_e32 v118, v109
	v_add_f32_e32 v106, 1.0, v106
	v_rcp_f32_e32 v107, v106
	v_mov_b32_e32 v106, v113
	v_pk_mul_f32 v[106:107], v[118:119], v[106:107]
	s_nop 0
	v_mul_f32_e32 v109, v106, v107
	v_mul_f32_e32 v106, v102, v122
	v_exp_f32_e32 v106, v106
	v_mov_b32_e32 v118, v98
	v_mul_f32_e32 v98, v103, v122
	v_exp_f32_e32 v98, v98
	v_add_f32_e32 v106, 1.0, v106
	v_rcp_f32_e32 v107, v106
	v_mov_b32_e32 v106, v102
	v_add_f32_e32 v98, 1.0, v98
	v_pk_mul_f32 v[106:107], v[118:119], v[106:107]
	s_nop 0
	v_mul_f32_e32 v112, v106, v107
	v_rcp_f32_e32 v107, v98
	v_mov_b32_e32 v118, v99
	v_mov_b32_e32 v106, v103
	v_lshl_add_u64 v[102:103], v[116:117], 0, v[114:115]
	v_pk_mul_f32 v[98:99], v[118:119], v[106:107]
	v_mov_b32_e32 v118, v100
	v_mul_f32_e32 v106, v98, v99
	v_mul_f32_e32 v98, v104, v122
	v_exp_f32_e32 v98, v98
	s_nop 0
	v_add_f32_e32 v98, 1.0, v98
	v_rcp_f32_e32 v99, v98
	v_mov_b32_e32 v98, v104
	v_pk_mul_f32 v[98:99], v[118:119], v[98:99]
	s_nop 0
	v_mul_f32_e32 v104, v98, v99
	v_mul_f32_e32 v98, v105, v122
	v_exp_f32_e32 v98, v98
	v_mov_b32_e32 v118, v101
	v_add_f32_e32 v98, 1.0, v98
	v_rcp_f32_e32 v99, v98
	v_mov_b32_e32 v98, v105
	v_pk_mul_f32 v[98:99], v[118:119], v[98:99]
	s_nop 0
	v_mul_f32_e32 v101, v98, v99
	v_cvt_pk_bf16_f32 v98, v110, v111
	v_cvt_pk_bf16_f32 v99, v108, v109
	v_cvt_pk_bf16_f32 v100, v112, v106
	v_cvt_pk_bf16_f32 v101, v104, v101
	flat_store_dwordx4 v[102:103], v[98:101]
	v_mov_b32_e32 v102, v94
	s_nop 0
	v_fmamk_f32 v100, v162, 0x3a000000, v223
	v_cmp_gt_f32_e32 vcc, s29, v100
	v_mul_f32_e32 v101, 0x4b800000, v100
	v_mad_i64_i32 v[98:99], s[2:3], v163, s34, v[140:141]
	v_cndmask_b32_e32 v100, v100, v101, vcc
	v_rsq_f32_e32 v100, v100
	s_nop 0
	v_mul_f32_e32 v101, 0x45800000, v100
	v_cndmask_b32_e32 v100, v100, v101, vcc
	v_mul_f32_e32 v104, 0xbfb8aa3b, v100
	v_mul_f32_e32 v101, v100, v100
	v_mul_f32_e32 v100, v94, v104
	v_exp_f32_e32 v100, v100
	s_nop 0
	v_add_f32_e32 v100, 1.0, v100
	v_rcp_f32_e32 v103, v100
	v_mov_b32_e32 v100, v90
	v_mul_f32_e32 v90, v95, v104
	v_exp_f32_e32 v90, v90
	v_pk_mul_f32 v[102:103], v[100:101], v[102:103]
	v_mov_b32_e32 v100, v91
	v_mul_f32_e32 v94, v102, v103
	v_add_f32_e32 v90, 1.0, v90
	v_rcp_f32_e32 v103, v90
	v_mov_b32_e32 v102, v95
	v_pk_mul_f32 v[90:91], v[100:101], v[102:103]
	s_nop 0
	v_mul_f32_e32 v95, v90, v91
	v_mul_f32_e32 v90, v96, v104
	v_exp_f32_e32 v90, v90
	v_mov_b32_e32 v100, v92
	v_add_f32_e32 v90, 1.0, v90
	v_rcp_f32_e32 v91, v90
	v_mov_b32_e32 v90, v96
	v_pk_mul_f32 v[90:91], v[100:101], v[90:91]
	s_nop 0
	v_mul_f32_e32 v92, v90, v91
	v_mul_f32_e32 v90, v97, v104
	v_exp_f32_e32 v90, v90
	v_mov_b32_e32 v100, v93
	v_add_f32_e32 v90, 1.0, v90
	v_rcp_f32_e32 v91, v90
	v_mov_b32_e32 v90, v97
	v_pk_mul_f32 v[90:91], v[100:101], v[90:91]
	s_nop 0
	v_mul_f32_e32 v93, v90, v91
	v_mul_f32_e32 v90, v86, v104
	v_exp_f32_e32 v90, v90
	v_mov_b32_e32 v100, v82
	v_mul_f32_e32 v82, v87, v104
	v_exp_f32_e32 v82, v82
	v_add_f32_e32 v90, 1.0, v90
	v_rcp_f32_e32 v91, v90
	v_mov_b32_e32 v90, v86
	v_add_f32_e32 v82, 1.0, v82
	v_pk_mul_f32 v[90:91], v[100:101], v[90:91]
	s_nop 0
	v_mul_f32_e32 v96, v90, v91
	v_rcp_f32_e32 v91, v82
	v_mov_b32_e32 v100, v83
	v_mov_b32_e32 v90, v87
	v_lshl_add_u64 v[86:87], v[98:99], 0, v[114:115]
	v_pk_mul_f32 v[82:83], v[100:101], v[90:91]
	v_mov_b32_e32 v100, v84
	v_mul_f32_e32 v90, v82, v83
	v_mul_f32_e32 v82, v88, v104
	v_exp_f32_e32 v82, v82
	s_nop 0
	v_add_f32_e32 v82, 1.0, v82
	v_rcp_f32_e32 v83, v82
	v_mov_b32_e32 v82, v88
	v_pk_mul_f32 v[82:83], v[100:101], v[82:83]
	s_nop 0
	v_mul_f32_e32 v88, v82, v83
	v_mul_f32_e32 v82, v89, v104
	v_exp_f32_e32 v82, v82
	v_mov_b32_e32 v100, v85
	v_add_f32_e32 v82, 1.0, v82
	v_rcp_f32_e32 v83, v82
	v_mov_b32_e32 v82, v89
	v_pk_mul_f32 v[82:83], v[100:101], v[82:83]
	s_nop 0
	v_mul_f32_e32 v85, v82, v83
	v_cvt_pk_bf16_f32 v82, v94, v95
	v_cvt_pk_bf16_f32 v83, v92, v93
	v_cvt_pk_bf16_f32 v84, v96, v90
; __device__ __forceinline__ unsigned pk2(float lo, float hi) { unsigned r; asm volatile("v_cvt_pk_bf16_f32 %0, %1, %2" : "=v"(r) : "v"(lo), "v"(hi)); return r; }
;     __device__ __forceinline__ void operator()(const f32x4 (&acc)[2][2][4][2], const Unit& u, int wr, int wc, int fr, int fq) const {
;     ...
; #pragma unroll
;         for (int ai = 0; ai < 2; ++ai)
; #pragma unroll
;             for (int m = 0; m < 4; ++m) { bf16_t* rowp = O + (size_t)(row0 + ai * HALF + m * 16) * DFF + col0; const float rsv = rsqrtf(rs[ai][m] * (1.f / D) + EPS);
;                 const float rs2 = rsv * rsv, nrs = -1.4426950409f * rsv;
;                 float v[8];
; #pragma unroll
;                 for (int n = 0; n < 2; ++n)
; #pragma unroll
;                     for (int j = 0; j < 4; ++j) {
;                         const float g0 = acc[ai][0][m][n][j], u0 = acc[ai][1][m][n][j];
;                         v[n * 4 + j] = (g0 * u0) * (rs2 * __builtin_amdgcn_rcpf(1.0f + __builtin_amdgcn_exp2f(g0 * nrs))); }
;                 u32x4 w; w.x = pk2(v[0], v[1]); w.y = pk2(v[2], v[3]); w.z = pk2(v[4], v[5]); w.w = pk2(v[6], v[7]);
;                 *(u32x4*)rowp = w; }
	v_cvt_pk_bf16_f32 v85, v88, v85
	flat_store_dwordx4 v[86:87], v[82:85]
	v_mov_b32_e32 v86, v78
	s_nop 0
	v_fmamk_f32 v84, v160, 0x3a000000, v223
	v_cmp_gt_f32_e32 vcc, s29, v84
	v_mul_f32_e32 v85, 0x4b800000, v84
	v_mad_i64_i32 v[82:83], s[2:3], v161, s34, v[140:141]
	v_cndmask_b32_e32 v84, v84, v85, vcc
	v_rsq_f32_e32 v84, v84
	s_nop 0
	v_mul_f32_e32 v85, 0x45800000, v84
	v_cndmask_b32_e32 v84, v84, v85, vcc
	v_mul_f32_e32 v88, 0xbfb8aa3b, v84
	v_mul_f32_e32 v85, v84, v84
	v_mul_f32_e32 v84, v78, v88
	v_exp_f32_e32 v84, v84
	s_nop 0
	v_add_f32_e32 v84, 1.0, v84
	v_rcp_f32_e32 v87, v84
	v_mov_b32_e32 v84, v74
	v_mul_f32_e32 v74, v79, v88
	v_exp_f32_e32 v74, v74
	v_pk_mul_f32 v[86:87], v[84:85], v[86:87]
	v_mov_b32_e32 v84, v75
	v_mul_f32_e32 v78, v86, v87
	v_add_f32_e32 v74, 1.0, v74
	v_rcp_f32_e32 v87, v74
	v_mov_b32_e32 v86, v79
	v_pk_mul_f32 v[74:75], v[84:85], v[86:87]
	s_nop 0
	v_mul_f32_e32 v79, v74, v75
	v_mul_f32_e32 v74, v80, v88
	v_exp_f32_e32 v74, v74
	v_mov_b32_e32 v84, v76
	v_add_f32_e32 v74, 1.0, v74
	v_rcp_f32_e32 v75, v74
	v_mov_b32_e32 v74, v80
	v_pk_mul_f32 v[74:75], v[84:85], v[74:75]
	s_nop 0
	v_mul_f32_e32 v76, v74, v75
	v_mul_f32_e32 v74, v81, v88
	v_exp_f32_e32 v74, v74
	v_mov_b32_e32 v84, v77
	v_add_f32_e32 v74, 1.0, v74
	v_rcp_f32_e32 v75, v74
	v_mov_b32_e32 v74, v81
	v_pk_mul_f32 v[74:75], v[84:85], v[74:75]
	s_nop 0
	v_mul_f32_e32 v77, v74, v75
	v_mul_f32_e32 v74, v70, v88
	v_exp_f32_e32 v74, v74
	v_mov_b32_e32 v84, v66
	v_mul_f32_e32 v66, v71, v88
	v_exp_f32_e32 v66, v66
	v_add_f32_e32 v74, 1.0, v74
	v_rcp_f32_e32 v75, v74
	v_mov_b32_e32 v74, v70
	v_add_f32_e32 v66, 1.0, v66
	v_pk_mul_f32 v[74:75], v[84:85], v[74:75]
	s_nop 0
	v_mul_f32_e32 v80, v74, v75
	v_rcp_f32_e32 v75, v66
	v_mov_b32_e32 v84, v67
	v_mov_b32_e32 v74, v71
	v_lshl_add_u64 v[70:71], v[82:83], 0, v[114:115]
	v_pk_mul_f32 v[66:67], v[84:85], v[74:75]
	v_mov_b32_e32 v84, v68
	v_mul_f32_e32 v74, v66, v67
	v_mul_f32_e32 v66, v72, v88
	v_exp_f32_e32 v66, v66
	s_nop 0
	v_add_f32_e32 v66, 1.0, v66
	v_rcp_f32_e32 v67, v66
	v_mov_b32_e32 v66, v72
	v_pk_mul_f32 v[66:67], v[84:85], v[66:67]
	s_nop 0
	v_mul_f32_e32 v72, v66, v67
	v_mul_f32_e32 v66, v73, v88
	v_exp_f32_e32 v66, v66
	v_mov_b32_e32 v84, v69
	v_add_f32_e32 v66, 1.0, v66
	v_rcp_f32_e32 v67, v66
	v_mov_b32_e32 v66, v73
	v_pk_mul_f32 v[66:67], v[84:85], v[66:67]
	s_nop 0
	v_mul_f32_e32 v69, v66, v67
	v_cvt_pk_bf16_f32 v66, v78, v79
	v_cvt_pk_bf16_f32 v67, v76, v77
	v_cvt_pk_bf16_f32 v68, v80, v74
	v_cvt_pk_bf16_f32 v69, v72, v69
	flat_store_dwordx4 v[70:71], v[66:69]
	v_mov_b32_e32 v70, v62
	s_nop 0
	v_fmamk_f32 v68, v158, 0x3a000000, v223
	v_cmp_gt_f32_e32 vcc, s29, v68
	v_mul_f32_e32 v69, 0x4b800000, v68
	v_mad_i64_i32 v[66:67], s[2:3], v159, s34, v[140:141]
	v_cndmask_b32_e32 v68, v68, v69, vcc
	v_rsq_f32_e32 v68, v68
	s_nop 0
	v_mul_f32_e32 v69, 0x45800000, v68
	v_cndmask_b32_e32 v68, v68, v69, vcc
	v_mul_f32_e32 v72, 0xbfb8aa3b, v68
	v_mul_f32_e32 v69, v68, v68
	v_mul_f32_e32 v68, v62, v72
	v_exp_f32_e32 v68, v68
	s_nop 0
	v_add_f32_e32 v68, 1.0, v68
	v_rcp_f32_e32 v71, v68
	v_mov_b32_e32 v68, v58
	v_mul_f32_e32 v58, v63, v72
	v_exp_f32_e32 v58, v58
	v_pk_mul_f32 v[70:71], v[68:69], v[70:71]
	v_mov_b32_e32 v68, v59
	v_mul_f32_e32 v62, v70, v71
	v_add_f32_e32 v58, 1.0, v58
	v_rcp_f32_e32 v71, v58
	v_mov_b32_e32 v70, v63
	v_pk_mul_f32 v[58:59], v[68:69], v[70:71]
	s_nop 0
	v_mul_f32_e32 v63, v58, v59
	v_mul_f32_e32 v58, v64, v72
	v_exp_f32_e32 v58, v58
	v_mov_b32_e32 v68, v60
	v_add_f32_e32 v58, 1.0, v58
	v_rcp_f32_e32 v59, v58
	v_mov_b32_e32 v58, v64
	v_pk_mul_f32 v[58:59], v[68:69], v[58:59]
	s_nop 0
	v_mul_f32_e32 v60, v58, v59
	v_mul_f32_e32 v58, v65, v72
	v_exp_f32_e32 v58, v58
	v_mov_b32_e32 v68, v61
	v_add_f32_e32 v58, 1.0, v58
	v_rcp_f32_e32 v59, v58
	v_mov_b32_e32 v58, v65
	v_pk_mul_f32 v[58:59], v[68:69], v[58:59]
	s_nop 0
	v_mul_f32_e32 v61, v58, v59
	v_mul_f32_e32 v58, v54, v72
	v_exp_f32_e32 v58, v58
	v_mov_b32_e32 v68, v50
	v_mul_f32_e32 v50, v55, v72
	v_exp_f32_e32 v50, v50
	v_add_f32_e32 v58, 1.0, v58
	v_rcp_f32_e32 v59, v58
	v_mov_b32_e32 v58, v54
	v_add_f32_e32 v50, 1.0, v50
	v_pk_mul_f32 v[58:59], v[68:69], v[58:59]
	s_nop 0
	v_mul_f32_e32 v64, v58, v59
	v_rcp_f32_e32 v59, v50
	v_mov_b32_e32 v68, v51
	v_mov_b32_e32 v58, v55
	v_lshl_add_u64 v[54:55], v[66:67], 0, v[114:115]
	v_pk_mul_f32 v[50:51], v[68:69], v[58:59]
	v_mov_b32_e32 v68, v52
	v_mul_f32_e32 v58, v50, v51
	v_mul_f32_e32 v50, v56, v72
	v_exp_f32_e32 v50, v50
	s_nop 0
	v_add_f32_e32 v50, 1.0, v50
	v_rcp_f32_e32 v51, v50
	v_mov_b32_e32 v50, v56
	v_pk_mul_f32 v[50:51], v[68:69], v[50:51]
	s_nop 0
	v_mul_f32_e32 v56, v50, v51
	v_mul_f32_e32 v50, v57, v72
	v_exp_f32_e32 v50, v50
	v_mov_b32_e32 v68, v53
	v_add_f32_e32 v50, 1.0, v50
	v_rcp_f32_e32 v51, v50
	v_mov_b32_e32 v50, v57
	v_pk_mul_f32 v[50:51], v[68:69], v[50:51]
	s_nop 0
	v_mul_f32_e32 v53, v50, v51
	v_cvt_pk_bf16_f32 v50, v62, v63
	v_cvt_pk_bf16_f32 v51, v60, v61
	v_cvt_pk_bf16_f32 v52, v64, v58
	v_cvt_pk_bf16_f32 v53, v56, v53
	flat_store_dwordx4 v[54:55], v[50:53]
	v_mov_b32_e32 v54, v46
	s_nop 0
	v_fmamk_f32 v52, v156, 0x3a000000, v223
	v_cmp_gt_f32_e32 vcc, s29, v52
	v_mul_f32_e32 v53, 0x4b800000, v52
	v_mad_i64_i32 v[50:51], s[2:3], v157, s34, v[140:141]
	v_cndmask_b32_e32 v52, v52, v53, vcc
	v_rsq_f32_e32 v52, v52
	s_nop 0
	v_mul_f32_e32 v53, 0x45800000, v52
	v_cndmask_b32_e32 v52, v52, v53, vcc
	v_mul_f32_e32 v56, 0xbfb8aa3b, v52
	v_mul_f32_e32 v53, v52, v52
	v_mul_f32_e32 v52, v46, v56
	v_exp_f32_e32 v52, v52
	s_nop 0
	v_add_f32_e32 v52, 1.0, v52
	v_rcp_f32_e32 v55, v52
	v_mov_b32_e32 v52, v42
	v_mul_f32_e32 v42, v47, v56
	v_exp_f32_e32 v42, v42
; __device__ __forceinline__ unsigned pk2(float lo, float hi) { unsigned r; asm volatile("v_cvt_pk_bf16_f32 %0, %1, %2" : "=v"(r) : "v"(lo), "v"(hi)); return r; }
; template <class Epi, class Sched, bool ALIGN_EPI = false, bool SP2 = false>
; __device__ __forceinline__ void gemm_phase(PG8_LAS unsigned char* lds, const Gemm g, const Sched& S, const Epi& E) {
;     ...
;         if (!has_next) break;
;     __device__ __forceinline__ void operator()(const f32x4 (&acc)[2][2][4][2], const Unit& u, int wr, int wc, int fr, int fq) const {
;     ...
; #pragma unroll
;         for (int ai = 0; ai < 2; ++ai)
; #pragma unroll
;             for (int m = 0; m < 4; ++m) { bf16_t* rowp = O + (size_t)(row0 + ai * HALF + m * 16) * DFF + col0; const float rsv = rsqrtf(rs[ai][m] * (1.f / D) + EPS);
;                 const float rs2 = rsv * rsv, nrs = -1.4426950409f * rsv;
;                 float v[8];
; #pragma unroll
;                 for (int n = 0; n < 2; ++n)
; #pragma unroll
;                     for (int j = 0; j < 4; ++j) {
;                         const float g0 = acc[ai][0][m][n][j], u0 = acc[ai][1][m][n][j];
;                         v[n * 4 + j] = (g0 * u0) * (rs2 * __builtin_amdgcn_rcpf(1.0f + __builtin_amdgcn_exp2f(g0 * nrs))); }
;                 u32x4 w; w.x = pk2(v[0], v[1]); w.y = pk2(v[2], v[3]); w.z = pk2(v[4], v[5]); w.w = pk2(v[6], v[7]);
;                 *(u32x4*)rowp = w; }
	v_pk_mul_f32 v[54:55], v[52:53], v[54:55]
	v_mov_b32_e32 v52, v43
	v_mul_f32_e32 v46, v54, v55
	v_add_f32_e32 v42, 1.0, v42
	v_rcp_f32_e32 v55, v42
	v_mov_b32_e32 v54, v47
	v_pk_mul_f32 v[42:43], v[52:53], v[54:55]
	s_nop 0
	v_mul_f32_e32 v47, v42, v43
	v_mul_f32_e32 v42, v48, v56
	v_exp_f32_e32 v42, v42
	v_mov_b32_e32 v52, v44
	v_add_f32_e32 v42, 1.0, v42
	v_rcp_f32_e32 v43, v42
	v_mov_b32_e32 v42, v48
	v_pk_mul_f32 v[42:43], v[52:53], v[42:43]
	s_nop 0
	v_mul_f32_e32 v44, v42, v43
	v_mul_f32_e32 v42, v49, v56
	v_exp_f32_e32 v42, v42
	v_mov_b32_e32 v52, v45
	v_add_f32_e32 v42, 1.0, v42
	v_rcp_f32_e32 v43, v42
	v_mov_b32_e32 v42, v49
	v_pk_mul_f32 v[42:43], v[52:53], v[42:43]
	s_nop 0
	v_mul_f32_e32 v45, v42, v43
	v_mul_f32_e32 v42, v38, v56
	v_exp_f32_e32 v42, v42
	v_mov_b32_e32 v52, v34
	v_mul_f32_e32 v34, v39, v56
	v_exp_f32_e32 v34, v34
	v_add_f32_e32 v42, 1.0, v42
	v_rcp_f32_e32 v43, v42
	v_mov_b32_e32 v42, v38
	v_add_f32_e32 v34, 1.0, v34
	v_pk_mul_f32 v[42:43], v[52:53], v[42:43]
	s_nop 0
	v_mul_f32_e32 v48, v42, v43
	v_rcp_f32_e32 v43, v34
	v_mov_b32_e32 v52, v35
	v_mov_b32_e32 v42, v39
	v_lshl_add_u64 v[38:39], v[50:51], 0, v[114:115]
	v_pk_mul_f32 v[34:35], v[52:53], v[42:43]
	v_mov_b32_e32 v52, v36
	v_mul_f32_e32 v42, v34, v35
	v_mul_f32_e32 v34, v40, v56
	v_exp_f32_e32 v34, v34
	s_nop 0
	v_add_f32_e32 v34, 1.0, v34
	v_rcp_f32_e32 v35, v34
	v_mov_b32_e32 v34, v40
	v_pk_mul_f32 v[34:35], v[52:53], v[34:35]
	s_nop 0
	v_mul_f32_e32 v40, v34, v35
	v_mul_f32_e32 v34, v41, v56
	v_exp_f32_e32 v34, v34
	v_mov_b32_e32 v52, v37
	v_add_f32_e32 v34, 1.0, v34
	v_rcp_f32_e32 v35, v34
	v_mov_b32_e32 v34, v41
	v_pk_mul_f32 v[34:35], v[52:53], v[34:35]
	s_nop 0
	v_mul_f32_e32 v37, v34, v35
	v_cvt_pk_bf16_f32 v34, v46, v47
	v_cvt_pk_bf16_f32 v35, v44, v45
	v_cvt_pk_bf16_f32 v36, v48, v42
	v_cvt_pk_bf16_f32 v37, v40, v37
	flat_store_dwordx4 v[38:39], v[34:37]
	v_mov_b32_e32 v38, v30
	s_nop 0
	v_fmamk_f32 v36, v154, 0x3a000000, v223
	v_cmp_gt_f32_e32 vcc, s29, v36
	v_mul_f32_e32 v37, 0x4b800000, v36
	v_mad_i64_i32 v[34:35], s[2:3], v155, s34, v[140:141]
	v_cndmask_b32_e32 v36, v36, v37, vcc
	v_rsq_f32_e32 v36, v36
	s_nop 0
	v_mul_f32_e32 v37, 0x45800000, v36
	v_cndmask_b32_e32 v36, v36, v37, vcc
	v_mul_f32_e32 v40, 0xbfb8aa3b, v36
	v_mul_f32_e32 v37, v36, v36
	v_mul_f32_e32 v36, v30, v40
	v_exp_f32_e32 v36, v36
	s_nop 0
	v_add_f32_e32 v36, 1.0, v36
	v_rcp_f32_e32 v39, v36
	v_mov_b32_e32 v36, v26
	v_mul_f32_e32 v26, v31, v40
	v_exp_f32_e32 v26, v26
	v_pk_mul_f32 v[38:39], v[36:37], v[38:39]
	v_mov_b32_e32 v36, v27
	v_mul_f32_e32 v30, v38, v39
	v_add_f32_e32 v26, 1.0, v26
	v_rcp_f32_e32 v39, v26
	v_mov_b32_e32 v38, v31
	v_pk_mul_f32 v[26:27], v[36:37], v[38:39]
	s_nop 0
	v_mul_f32_e32 v31, v26, v27
	v_mul_f32_e32 v26, v32, v40
	v_exp_f32_e32 v26, v26
	v_mov_b32_e32 v36, v28
	v_add_f32_e32 v26, 1.0, v26
	v_rcp_f32_e32 v27, v26
	v_mov_b32_e32 v26, v32
	v_pk_mul_f32 v[26:27], v[36:37], v[26:27]
	s_nop 0
	v_mul_f32_e32 v28, v26, v27
	v_mul_f32_e32 v26, v33, v40
	v_exp_f32_e32 v26, v26
	v_mov_b32_e32 v36, v29
	v_add_f32_e32 v26, 1.0, v26
	v_rcp_f32_e32 v27, v26
	v_mov_b32_e32 v26, v33
	v_pk_mul_f32 v[26:27], v[36:37], v[26:27]
	s_nop 0
	v_mul_f32_e32 v29, v26, v27
	v_mul_f32_e32 v26, v22, v40
	v_exp_f32_e32 v26, v26
	v_mov_b32_e32 v36, v18
	v_mul_f32_e32 v18, v23, v40
	v_exp_f32_e32 v18, v18
	v_add_f32_e32 v26, 1.0, v26
	v_rcp_f32_e32 v27, v26
	v_mov_b32_e32 v26, v22
	v_add_f32_e32 v18, 1.0, v18
	v_pk_mul_f32 v[26:27], v[36:37], v[26:27]
	s_nop 0
	v_mul_f32_e32 v32, v26, v27
	v_rcp_f32_e32 v27, v18
	v_mov_b32_e32 v36, v19
	v_mov_b32_e32 v26, v23
	v_lshl_add_u64 v[22:23], v[34:35], 0, v[114:115]
	v_pk_mul_f32 v[18:19], v[36:37], v[26:27]
	v_mov_b32_e32 v36, v20
	v_mul_f32_e32 v26, v18, v19
	v_mul_f32_e32 v18, v24, v40
	v_exp_f32_e32 v18, v18
	s_nop 0
	v_add_f32_e32 v18, 1.0, v18
	v_rcp_f32_e32 v19, v18
	v_mov_b32_e32 v18, v24
	v_pk_mul_f32 v[18:19], v[36:37], v[18:19]
	s_nop 0
	v_mul_f32_e32 v24, v18, v19
	v_mul_f32_e32 v18, v25, v40
	v_exp_f32_e32 v18, v18
	v_mov_b32_e32 v36, v21
	v_add_f32_e32 v18, 1.0, v18
	v_rcp_f32_e32 v19, v18
	v_mov_b32_e32 v18, v25
	v_pk_mul_f32 v[18:19], v[36:37], v[18:19]
	s_nop 0
	v_mul_f32_e32 v21, v18, v19
	v_cvt_pk_bf16_f32 v18, v30, v31
	v_cvt_pk_bf16_f32 v19, v28, v29
	v_cvt_pk_bf16_f32 v20, v32, v26
	v_cvt_pk_bf16_f32 v21, v24, v21
	flat_store_dwordx4 v[22:23], v[18:21]
	v_mov_b32_e32 v22, v14
	s_nop 0
	v_fmamk_f32 v20, v152, 0x3a000000, v223
	v_cmp_gt_f32_e32 vcc, s29, v20
	v_mul_f32_e32 v21, 0x4b800000, v20
	v_mad_i64_i32 v[18:19], s[2:3], v153, s34, v[140:141]
	v_cndmask_b32_e32 v20, v20, v21, vcc
	v_rsq_f32_e32 v20, v20
	s_nop 0
	v_mul_f32_e32 v21, 0x45800000, v20
	v_cndmask_b32_e32 v20, v20, v21, vcc
	v_mul_f32_e32 v24, 0xbfb8aa3b, v20
	v_mul_f32_e32 v21, v20, v20
	v_mul_f32_e32 v20, v14, v24
	v_exp_f32_e32 v20, v20
	s_andn2_b64 vcc, exec, s[40:41]
	v_add_f32_e32 v20, 1.0, v20
	v_rcp_f32_e32 v23, v20
	v_mov_b32_e32 v20, v10
	v_mul_f32_e32 v10, v15, v24
	v_exp_f32_e32 v10, v10
	v_pk_mul_f32 v[22:23], v[20:21], v[22:23]
	v_mov_b32_e32 v20, v11
	v_mul_f32_e32 v14, v22, v23
	v_add_f32_e32 v10, 1.0, v10
	v_rcp_f32_e32 v23, v10
	v_mov_b32_e32 v22, v15
	v_pk_mul_f32 v[10:11], v[20:21], v[22:23]
	s_nop 0
	v_mul_f32_e32 v15, v10, v11
	v_mul_f32_e32 v10, v16, v24
	v_exp_f32_e32 v10, v10
	v_mov_b32_e32 v20, v12
	v_add_f32_e32 v10, 1.0, v10
	v_rcp_f32_e32 v11, v10
	v_mov_b32_e32 v10, v16
	v_pk_mul_f32 v[10:11], v[20:21], v[10:11]
	s_nop 0
	v_mul_f32_e32 v12, v10, v11
	v_mul_f32_e32 v10, v17, v24
	v_exp_f32_e32 v10, v10
	v_mov_b32_e32 v20, v13
	v_add_f32_e32 v10, 1.0, v10
	v_rcp_f32_e32 v11, v10
	v_mov_b32_e32 v10, v17
	v_pk_mul_f32 v[10:11], v[20:21], v[10:11]
	s_nop 0
	v_mul_f32_e32 v13, v10, v11
	v_mul_f32_e32 v10, v6, v24
	v_exp_f32_e32 v10, v10
	v_mov_b32_e32 v20, v2
	v_mul_f32_e32 v2, v7, v24
	v_exp_f32_e32 v2, v2
	v_add_f32_e32 v10, 1.0, v10
	v_rcp_f32_e32 v11, v10
	v_mov_b32_e32 v10, v6
	v_add_f32_e32 v2, 1.0, v2
	v_pk_mul_f32 v[10:11], v[20:21], v[10:11]
	s_nop 0
	v_mul_f32_e32 v16, v10, v11
	v_rcp_f32_e32 v11, v2
	v_mov_b32_e32 v20, v3
	v_mov_b32_e32 v10, v7
	v_lshl_add_u64 v[6:7], v[18:19], 0, v[114:115]
	v_pk_mul_f32 v[2:3], v[20:21], v[10:11]
	v_mov_b32_e32 v20, v4
	v_mul_f32_e32 v10, v2, v3
	v_mul_f32_e32 v2, v8, v24
	v_exp_f32_e32 v2, v2
	s_nop 0
	v_add_f32_e32 v2, 1.0, v2
	v_rcp_f32_e32 v3, v2
	v_mov_b32_e32 v2, v8
	v_pk_mul_f32 v[2:3], v[20:21], v[2:3]
	s_nop 0
	v_mul_f32_e32 v8, v2, v3
	v_mul_f32_e32 v2, v9, v24
	v_exp_f32_e32 v2, v2
	v_mov_b32_e32 v20, v5
	v_add_f32_e32 v2, 1.0, v2
	v_rcp_f32_e32 v3, v2
	v_mov_b32_e32 v2, v9
	v_pk_mul_f32 v[2:3], v[20:21], v[2:3]
	s_nop 0
	v_mul_f32_e32 v5, v2, v3
	v_cvt_pk_bf16_f32 v2, v14, v15
	v_cvt_pk_bf16_f32 v3, v12, v13
	v_cvt_pk_bf16_f32 v4, v16, v10
	v_cvt_pk_bf16_f32 v5, v8, v5
	flat_store_dwordx4 v[6:7], v[2:5]
	s_cbranch_vccnz .LBB0_1483
; #define PG8_BAR __builtin_amdgcn_s_barrier()
; template <class Epi, class Sched, bool ALIGN_EPI = false, bool SP2 = false>
; __device__ __forceinline__ void gemm_phase(PG8_LAS unsigned char* lds, const Gemm g, const Sched& S, const Epi& E) {
;     ...
;         if (!has_next) break;
;         if (cur.ks != -2) {
; #pragma unroll
;         for (int a = 0; a < 2; ++a)
; #pragma unroll
;             for (int b = 0; b < 2; ++b)
; #pragma unroll
;                 for (int m = 0; m < 4; ++m)
; #pragma unroll
;                     for (int n = 0; n < 2; ++n) acc[a][b][m][n] = (f32x4){0.f, 0.f, 0.f, 0.f};
;         }
;         cur = nxt; cA = nA; cB = nB; ++ui;
;         if constexpr (ALIGN_EPI) { if (wr == 1) PG8_BAR; }
	s_andn2_b64 vcc, exec, s[14:15]
	s_cbranch_vccnz .LBB0_1482
	s_barrier
	s_branch .LBB0_1482
	s_nop 0
	s_nop 0
	s_nop 0
	s_nop 0
	s_nop 0
	s_nop 0
	s_nop 0
	s_nop 0
	s_nop 0
	s_nop 0
	s_nop 0
	s_nop 0
	s_nop 0
	s_nop 0
	s_nop 0
